# combo1 + GEMM4 epilogue h1 loads batched + sample-scan items rebalanced to GEMM-less workgroups
# speedup vs baseline: 1.0236x; 1.0067x over previous
; __device__ __forceinline__ void phase_scan(const Params& p, LAS unsigned char* lds) {
;     ...
;         for (int s2 = bi; s2 < 256; s2 += nb) { const int s = s2 >> 1, half = s2 & 1, b = s >> 2, h = s & 3;
;             scan_block<false>(p, lds, 1024 + s, 1, p.in[4] + (size_t)s * 16384, p.out + O_SBS + (size_t)s * 16384, MP + b * 16, 16, h, half); }
;     ...
;         { pg8::StaticOrder S; pg8::Gemm g{(const bf16_t*)(p.ws + WS_XN), (const bf16_t*)(p.ws + WS_WT_IN) + (size_t)ZC_BG * 1024, MTOK, 512, 1024, 1024, 0}; S.init(MTOK, 512, nb, bi);
;           pg8::EpiZ E{(bf16_t*)(p.ws + WS_Z) + ZC_BG, NZ}; pg8::gemm_phase(lds, g, S, E); }
.LBB0_444:
	s_or_b64 exec, exec, s[10:11]
	s_add_i32 s40, s40, 60
	s_addk_i32 s28, 0xf00
	s_addk_i32 s34, 0x78
	s_cmpk_gt_i32 s40, 0xff
	s_cbranch_scc1 .LBB0_512
	s_cmpk_lt_i32 s40, 0xc0
	s_cbranch_scc1 .LBB0_512

; #define PG8_STAGE(bufoff, gbase, voff) do { _Pragma("unroll") for (int _i = 0; _i < 2; ++_i) \
;         __builtin_amdgcn_global_load_lds((const unsigned*)((const char*)(gbase) + (voff)[_i]), (LAS unsigned*)(lds + (bufoff) + ldsw + _i * 8192), 16, 0, 0); } while (0)
; #define PG8_LDA(dst, b, h) do { _Pragma("unroll") for (int m = 0; m < 4; ++m) _Pragma("unroll") for (int k = 0; k < 2; ++k) dst[m][k] = *(const LAS bf16x8*)(lds + PG8_SA(b, h) + aoff + m * 2048 + k * 1024); } while (0)
; #define PG8_LDB(dst, b, h) do { _Pragma("unroll") for (int n = 0; n < 2; ++n) _Pragma("unroll") for (int k = 0; k < 2; ++k) dst[n][k] = *(const LAS bf16x8*)(lds + PG8_SB(b, h) + boff + n * 2048 + k * 1024); } while (0)
; #define PG8_MMA(ai, bj, At, Bt) do { __builtin_amdgcn_s_setprio(1); _Pragma("unroll") for (int m = 0; m < 4; ++m) _Pragma("unroll") for (int n = 0; n < 2; ++n) _Pragma("unroll") for (int k = 0; k < 2; ++k) \
;         acc[ai][bj][m][n] = __builtin_amdgcn_mfma_f32_16x16x32_bf16(Bt[n][k], At[m][k], acc[ai][bj][m][n], 0, 0, 0); __builtin_amdgcn_s_setprio(0); } while (0)
; #define PG8_WAIT_L(n) asm volatile("s_waitcnt lgkmcnt(" #n ")" ::: "memory")
; #define PG8_BAR __builtin_amdgcn_s_barrier()
; #define PG8_SCHED __builtin_amdgcn_sched_barrier(0)
; template <class Epi>
; __device__ __forceinline__ void gemm_phase(LAS unsigned char* lds, const Gemm g, const StaticOrder& S, const Epi& E) {
;     ...
;             PG8_LDB(B0, 0, 0); PG8_SCHED; PG8_LDA(At, 0, 0); PG8_STAGE(PG8_SA(1, 1), a1 + hstepA, voffA);
;             PG8_WAIT_L(8); PG8_BAR; PG8_WAIT_L(0); PG8_MMA(0, 0, At, B0); PG8_BAR; PG8_SCHED;
;             PG8_LDB(B1, 0, 1); PG8_STAGE(PG8_SB(0, 0), b2, voffB);
;             PG8_BAR; PG8_WAIT_L(0); PG8_MMA(0, 1, At, B1); PG8_BAR;
;             PG8_LDA(At, 0, 1); PG8_STAGE(PG8_SA(0, 0), a2, voffA);
;             PG8_BAR; PG8_WAIT_L(0); PG8_MMA(1, 0, At, B0); PG8_BAR; PG8_SCHED;
.LBB0_1478:
	ds_read_b128 v[140:143], v150
	ds_read_b128 v[154:157], v150 offset:1024
	ds_read_b128 v[158:161], v150 offset:2048
	ds_read_b128 v[162:165], v150 offset:3072
	s_add_u32 s38, s36, 0xfffc0080
	s_addc_u32 s39, s37, -1
	s_cmp_eq_u32 s59, 12
	s_cselect_b32 s41, s25, s39
	s_cselect_b32 s40, s55, s38
	s_cselect_b32 s39, s23, s58
	s_cselect_b32 s38, s56, s57
	v_lshl_add_u64 v[144:145], s[36:37], 0, v[132:133]
	s_add_i32 m0, s35, 0xc000
	ds_read_b128 v[166:169], v151
	ds_read_b128 v[170:173], v151 offset:1024
	ds_read_b128 v[174:177], v151 offset:2048
	ds_read_b128 v[178:181], v151 offset:3072
	ds_read_b128 v[186:189], v151 offset:4096
	ds_read_b128 v[190:193], v151 offset:5120
	ds_read_b128 v[194:197], v151 offset:6144
	ds_read_b128 v[198:201], v151 offset:7168
	global_load_lds_dwordx4 v[144:145], off
	v_lshl_add_u64 v[144:145], s[36:37], 0, v[134:135]
	s_add_i32 m0, s35, 0xe000
	s_nop 0
	global_load_lds_dwordx4 v[144:145], off
	s_waitcnt lgkmcnt(8)
	s_barrier
	s_waitcnt lgkmcnt(0)
	s_setprio 1
	s_waitcnt lgkmcnt(0)
	v_mfma_f32_16x16x32_bf16 v[124:127], v[140:143], v[166:169], v[124:127]
	v_mfma_f32_16x16x32_bf16 v[120:123], v[158:161], v[166:169], v[120:123]
	v_mfma_f32_16x16x32_bf16 v[112:115], v[140:143], v[174:177], v[112:115]
	v_mfma_f32_16x16x32_bf16 v[104:107], v[158:161], v[174:177], v[104:107]
	v_mfma_f32_16x16x32_bf16 v[96:99], v[140:143], v[186:189], v[96:99]
	v_mfma_f32_16x16x32_bf16 v[88:91], v[158:161], v[186:189], v[88:91]
	v_mfma_f32_16x16x32_bf16 v[80:83], v[140:143], v[194:197], v[80:83]
	v_mfma_f32_16x16x32_bf16 v[72:75], v[158:161], v[194:197], v[72:75]
	v_mfma_f32_16x16x32_bf16 v[124:127], v[154:157], v[170:173], v[124:127]
	v_mfma_f32_16x16x32_bf16 v[120:123], v[162:165], v[170:173], v[120:123]
	v_mfma_f32_16x16x32_bf16 v[112:115], v[154:157], v[178:181], v[112:115]
	v_mfma_f32_16x16x32_bf16 v[104:107], v[162:165], v[178:181], v[104:107]
	v_mfma_f32_16x16x32_bf16 v[96:99], v[154:157], v[190:193], v[96:99]
	v_mfma_f32_16x16x32_bf16 v[88:91], v[162:165], v[190:193], v[88:91]
	v_mfma_f32_16x16x32_bf16 v[80:83], v[154:157], v[198:201], v[80:83]
	v_mfma_f32_16x16x32_bf16 v[72:75], v[162:165], v[198:201], v[72:75]
	s_setprio 0
	s_barrier
	s_add_i32 s60, s52, s42
	v_lshl_add_u64 v[144:145], s[38:39], 0, v[128:129]
	s_mov_b32 m0, s60
	ds_read_b128 v[202:205], v152
	ds_read_b128 v[206:209], v152 offset:1024
	ds_read_b128 v[210:213], v152 offset:2048
	ds_read_b128 v[214:217], v152 offset:3072
	global_load_lds_dwordx4 v[144:145], off
	v_lshl_add_u64 v[182:183], s[38:39], 0, v[130:131]
	s_add_i32 m0, s60, 0x2000
	s_nop 0
	global_load_lds_dwordx4 v[182:183], off
	s_barrier
	s_waitcnt lgkmcnt(0)
	s_setprio 1
	s_waitcnt lgkmcnt(0)
	v_mfma_f32_16x16x32_bf16 v[116:119], v[202:205], v[166:169], v[116:119]
	v_mfma_f32_16x16x32_bf16 v[108:111], v[210:213], v[166:169], v[108:111]
	v_mfma_f32_16x16x32_bf16 v[100:103], v[202:205], v[174:177], v[100:103]
	v_mfma_f32_16x16x32_bf16 v[92:95], v[210:213], v[174:177], v[92:95]
	v_mfma_f32_16x16x32_bf16 v[84:87], v[202:205], v[186:189], v[84:87]
	v_mfma_f32_16x16x32_bf16 v[76:79], v[210:213], v[186:189], v[76:79]
	v_mfma_f32_16x16x32_bf16 v[68:71], v[202:205], v[194:197], v[68:71]
	v_mfma_f32_16x16x32_bf16 v[64:67], v[210:213], v[194:197], v[64:67]
	v_mfma_f32_16x16x32_bf16 v[116:119], v[206:209], v[170:173], v[116:119]
	v_mfma_f32_16x16x32_bf16 v[108:111], v[214:217], v[170:173], v[108:111]
	v_mfma_f32_16x16x32_bf16 v[100:103], v[206:209], v[178:181], v[100:103]
	v_mfma_f32_16x16x32_bf16 v[92:95], v[214:217], v[178:181], v[92:95]
	v_mfma_f32_16x16x32_bf16 v[84:87], v[206:209], v[190:193], v[84:87]
	v_mfma_f32_16x16x32_bf16 v[76:79], v[214:217], v[190:193], v[76:79]
	v_mfma_f32_16x16x32_bf16 v[68:71], v[206:209], v[198:201], v[68:71]
	v_mfma_f32_16x16x32_bf16 v[64:67], v[214:217], v[198:201], v[64:67]
	s_setprio 0
	s_mov_b32 m0, s35
	v_lshl_add_u64 v[218:219], s[40:41], 0, v[128:129]
	s_barrier
	ds_read_b128 v[166:169], v151 offset:16384
	ds_read_b128 v[170:173], v151 offset:17408
	ds_read_b128 v[174:177], v151 offset:18432
	ds_read_b128 v[178:181], v151 offset:19456
	ds_read_b128 v[186:189], v151 offset:20480
	ds_read_b128 v[190:193], v151 offset:21504
	ds_read_b128 v[194:197], v151 offset:22528
	ds_read_b128 v[198:201], v151 offset:23552
	global_load_lds_dwordx4 v[218:219], off
	v_lshl_add_u64 v[220:221], s[40:41], 0, v[130:131]
	s_mov_b32 m0, s43
	s_nop 0
	global_load_lds_dwordx4 v[220:221], off
	s_barrier
	s_waitcnt lgkmcnt(0)
	s_setprio 1
	s_waitcnt lgkmcnt(0)
	v_mfma_f32_16x16x32_bf16 v[60:63], v[140:143], v[166:169], v[60:63]
	v_mfma_f32_16x16x32_bf16 v[56:59], v[158:161], v[166:169], v[56:59]
	v_mfma_f32_16x16x32_bf16 v[48:51], v[140:143], v[174:177], v[48:51]
	v_mfma_f32_16x16x32_bf16 v[40:43], v[158:161], v[174:177], v[40:43]
	v_mfma_f32_16x16x32_bf16 v[32:35], v[140:143], v[186:189], v[32:35]
	v_mfma_f32_16x16x32_bf16 v[24:27], v[158:161], v[186:189], v[24:27]
	v_mfma_f32_16x16x32_bf16 v[16:19], v[140:143], v[194:197], v[16:19]
	v_mfma_f32_16x16x32_bf16 v[8:11], v[158:161], v[194:197], v[8:11]
	v_mfma_f32_16x16x32_bf16 v[60:63], v[154:157], v[170:173], v[60:63]
	v_mfma_f32_16x16x32_bf16 v[56:59], v[162:165], v[170:173], v[56:59]
	v_mfma_f32_16x16x32_bf16 v[48:51], v[154:157], v[178:181], v[48:51]
	v_mfma_f32_16x16x32_bf16 v[40:43], v[162:165], v[178:181], v[40:43]
	v_mfma_f32_16x16x32_bf16 v[32:35], v[154:157], v[190:193], v[32:35]
	v_mfma_f32_16x16x32_bf16 v[24:27], v[162:165], v[190:193], v[24:27]
	v_mfma_f32_16x16x32_bf16 v[16:19], v[154:157], v[198:201], v[16:19]
	v_mfma_f32_16x16x32_bf16 v[8:11], v[162:165], v[198:201], v[8:11]
	s_setprio 0
	s_barrier
; #define PG8_STAGE(bufoff, gbase, voff) do { _Pragma("unroll") for (int _i = 0; _i < 2; ++_i) \
;         __builtin_amdgcn_global_load_lds((const unsigned*)((const char*)(gbase) + (voff)[_i]), (LAS unsigned*)(lds + (bufoff) + ldsw + _i * 8192), 16, 0, 0); } while (0)
; #define PG8_LDA(dst, b, h) do { _Pragma("unroll") for (int m = 0; m < 4; ++m) _Pragma("unroll") for (int k = 0; k < 2; ++k) dst[m][k] = *(const LAS bf16x8*)(lds + PG8_SA(b, h) + aoff + m * 2048 + k * 1024); } while (0)
; #define PG8_LDB(dst, b, h) do { _Pragma("unroll") for (int n = 0; n < 2; ++n) _Pragma("unroll") for (int k = 0; k < 2; ++k) dst[n][k] = *(const LAS bf16x8*)(lds + PG8_SB(b, h) + boff + n * 2048 + k * 1024); } while (0)
; #define PG8_MMA(ai, bj, At, Bt) do { __builtin_amdgcn_s_setprio(1); _Pragma("unroll") for (int m = 0; m < 4; ++m) _Pragma("unroll") for (int n = 0; n < 2; ++n) _Pragma("unroll") for (int k = 0; k < 2; ++k) \
;         acc[ai][bj][m][n] = __builtin_amdgcn_mfma_f32_16x16x32_bf16(Bt[n][k], At[m][k], acc[ai][bj][m][n], 0, 0, 0); __builtin_amdgcn_s_setprio(0); } while (0)
; #define PG8_WAIT_V(n) asm volatile("s_waitcnt vmcnt(" #n ")" ::: "memory")
; #define PG8_WAIT_L(n) asm volatile("s_waitcnt lgkmcnt(" #n ")" ::: "memory")
; #define PG8_BAR __builtin_amdgcn_s_barrier()
; #define PG8_SCHED __builtin_amdgcn_sched_barrier(0)
; template <class Epi>
; __device__ __forceinline__ void gemm_phase(LAS unsigned char* lds, const Gemm g, const StaticOrder& S, const Epi& E) {
;     ...
;             PG8_STAGE(PG8_SB(0, 1), b2 + hstepB, voffB);
;             PG8_WAIT_V(6); PG8_BAR; PG8_MMA(1, 1, At, B1); PG8_BAR;
;             PG8_LDB(B0, 1, 0); PG8_SCHED; PG8_LDA(At, 1, 0); PG8_STAGE(PG8_SA(0, 1), a2 + hstepA, voffA);
;             PG8_WAIT_L(8); PG8_BAR; PG8_WAIT_L(0); PG8_MMA(0, 0, At, B0); PG8_BAR; PG8_SCHED;
;             PG8_LDB(B1, 1, 1); PG8_STAGE(PG8_SB(1, 0), b3, voffB);
;             PG8_BAR; PG8_WAIT_L(0); PG8_MMA(0, 1, At, B1); PG8_BAR;
;             PG8_LDA(At, 1, 1); PG8_STAGE(PG8_SA(1, 0), a3, voffA);
	s_add_u32 s60, s38, 0x40000
	s_addc_u32 s61, s39, 0
	s_add_i32 s62, s53, s42
	v_lshl_add_u64 v[140:141], s[60:61], 0, v[128:129]
	s_mov_b32 m0, s62
	s_nop 0
	global_load_lds_dwordx4 v[140:141], off
	v_lshl_add_u64 v[140:141], s[60:61], 0, v[130:131]
	s_add_i32 m0, s62, 0x2000
	s_nop 0
	global_load_lds_dwordx4 v[140:141], off
	s_waitcnt vmcnt(6)
	s_barrier
	s_setprio 1
	v_mfma_f32_16x16x32_bf16 v[52:55], v[202:205], v[166:169], v[52:55]
	v_mfma_f32_16x16x32_bf16 v[44:47], v[210:213], v[166:169], v[44:47]
	v_mfma_f32_16x16x32_bf16 v[36:39], v[202:205], v[174:177], v[36:39]
	v_mfma_f32_16x16x32_bf16 v[28:31], v[210:213], v[174:177], v[28:31]
	v_mfma_f32_16x16x32_bf16 v[20:23], v[202:205], v[186:189], v[20:23]
	v_mfma_f32_16x16x32_bf16 v[12:15], v[210:213], v[186:189], v[12:15]
	v_mfma_f32_16x16x32_bf16 v[4:7], v[202:205], v[194:197], v[4:7]
	v_mfma_f32_16x16x32_bf16 v[0:3], v[210:213], v[194:197], v[0:3]
	v_mfma_f32_16x16x32_bf16 v[52:55], v[206:209], v[170:173], v[52:55]
	v_mfma_f32_16x16x32_bf16 v[44:47], v[214:217], v[170:173], v[44:47]
	v_mfma_f32_16x16x32_bf16 v[36:39], v[206:209], v[178:181], v[36:39]
	v_mfma_f32_16x16x32_bf16 v[28:31], v[214:217], v[178:181], v[28:31]
	v_mfma_f32_16x16x32_bf16 v[20:23], v[206:209], v[190:193], v[20:23]
	v_mfma_f32_16x16x32_bf16 v[12:15], v[214:217], v[190:193], v[12:15]
	v_mfma_f32_16x16x32_bf16 v[4:7], v[206:209], v[198:201], v[4:7]
	v_mfma_f32_16x16x32_bf16 v[0:3], v[214:217], v[198:201], v[0:3]
	s_setprio 0
	s_add_i32 s60, 0, 0x18000
	v_add_u32_e32 v153, s60, v148
	s_barrier
	ds_read_b128 v[140:143], v153
	ds_read_b128 v[154:157], v153 offset:1024
	ds_read_b128 v[158:161], v153 offset:2048
	ds_read_b128 v[162:165], v153 offset:3072
	s_add_u32 s40, s40, 0x40000
	s_addc_u32 s41, s41, 0
	s_mov_b32 m0, s44
	v_lshl_add_u64 v[202:203], s[40:41], 0, v[128:129]
	ds_read_b128 v[166:169], v151 offset:32768
	ds_read_b128 v[170:173], v151 offset:33792
	ds_read_b128 v[174:177], v151 offset:34816
	ds_read_b128 v[178:181], v151 offset:35840
	ds_read_b128 v[186:189], v151 offset:36864
	ds_read_b128 v[190:193], v151 offset:37888
	ds_read_b128 v[194:197], v151 offset:38912
	ds_read_b128 v[198:201], v151 offset:39936
	global_load_lds_dwordx4 v[202:203], off
	v_lshl_add_u64 v[202:203], s[40:41], 0, v[130:131]
	s_mov_b32 m0, s45
	s_nop 0
	global_load_lds_dwordx4 v[202:203], off
	s_waitcnt lgkmcnt(8)
	s_barrier
	s_waitcnt lgkmcnt(0)
	s_setprio 1
	s_waitcnt lgkmcnt(0)
	v_mfma_f32_16x16x32_bf16 v[124:127], v[140:143], v[166:169], v[124:127]
	v_mfma_f32_16x16x32_bf16 v[120:123], v[158:161], v[166:169], v[120:123]
	v_mfma_f32_16x16x32_bf16 v[112:115], v[140:143], v[174:177], v[112:115]
	v_mfma_f32_16x16x32_bf16 v[104:107], v[158:161], v[174:177], v[104:107]
	v_mfma_f32_16x16x32_bf16 v[96:99], v[140:143], v[186:189], v[96:99]
	v_mfma_f32_16x16x32_bf16 v[88:91], v[158:161], v[186:189], v[88:91]
	v_mfma_f32_16x16x32_bf16 v[80:83], v[140:143], v[194:197], v[80:83]
	v_mfma_f32_16x16x32_bf16 v[72:75], v[158:161], v[194:197], v[72:75]
	v_mfma_f32_16x16x32_bf16 v[124:127], v[154:157], v[170:173], v[124:127]
	v_mfma_f32_16x16x32_bf16 v[120:123], v[162:165], v[170:173], v[120:123]
	v_mfma_f32_16x16x32_bf16 v[112:115], v[154:157], v[178:181], v[112:115]
	v_mfma_f32_16x16x32_bf16 v[104:107], v[162:165], v[178:181], v[104:107]
	v_mfma_f32_16x16x32_bf16 v[96:99], v[154:157], v[190:193], v[96:99]
	v_mfma_f32_16x16x32_bf16 v[88:91], v[162:165], v[190:193], v[88:91]
	v_mfma_f32_16x16x32_bf16 v[80:83], v[154:157], v[198:201], v[80:83]
	v_mfma_f32_16x16x32_bf16 v[72:75], v[162:165], v[198:201], v[72:75]
	s_setprio 0
	s_barrier
	s_add_i32 s40, 0, 0x1c000
	s_add_i32 s41, s60, s42
	v_add_u32_e32 v153, s40, v148
	v_lshl_add_u64 v[144:145], v[144:145], 0, s[12:13]
	s_mov_b32 m0, s41
	ds_read_b128 v[202:205], v153
	ds_read_b128 v[206:209], v153 offset:1024
	ds_read_b128 v[210:213], v153 offset:2048
	ds_read_b128 v[214:217], v153 offset:3072
	global_load_lds_dwordx4 v[144:145], off
	v_lshl_add_u64 v[144:145], v[182:183], 0, s[12:13]
	s_add_i32 m0, s41, 0x2000
	s_nop 0
	global_load_lds_dwordx4 v[144:145], off
	s_barrier
	s_waitcnt lgkmcnt(0)
	s_setprio 1
	s_waitcnt lgkmcnt(0)
	v_mfma_f32_16x16x32_bf16 v[116:119], v[202:205], v[166:169], v[116:119]
	v_mfma_f32_16x16x32_bf16 v[108:111], v[210:213], v[166:169], v[108:111]
	v_mfma_f32_16x16x32_bf16 v[100:103], v[202:205], v[174:177], v[100:103]
	v_mfma_f32_16x16x32_bf16 v[92:95], v[210:213], v[174:177], v[92:95]
	v_mfma_f32_16x16x32_bf16 v[84:87], v[202:205], v[186:189], v[84:87]
	v_mfma_f32_16x16x32_bf16 v[76:79], v[210:213], v[186:189], v[76:79]
	v_mfma_f32_16x16x32_bf16 v[68:71], v[202:205], v[194:197], v[68:71]
	v_mfma_f32_16x16x32_bf16 v[64:67], v[210:213], v[194:197], v[64:67]
	v_mfma_f32_16x16x32_bf16 v[116:119], v[206:209], v[170:173], v[116:119]
	v_mfma_f32_16x16x32_bf16 v[108:111], v[214:217], v[170:173], v[108:111]
	v_mfma_f32_16x16x32_bf16 v[100:103], v[206:209], v[178:181], v[100:103]
	v_mfma_f32_16x16x32_bf16 v[92:95], v[214:217], v[178:181], v[92:95]
	v_mfma_f32_16x16x32_bf16 v[84:87], v[206:209], v[190:193], v[84:87]
	v_mfma_f32_16x16x32_bf16 v[76:79], v[214:217], v[190:193], v[76:79]
	v_mfma_f32_16x16x32_bf16 v[68:71], v[206:209], v[198:201], v[68:71]
	v_mfma_f32_16x16x32_bf16 v[64:67], v[214:217], v[198:201], v[64:67]
	s_setprio 0
	s_mov_b32 m0, s47
	v_lshl_add_u64 v[144:145], v[218:219], 0, s[12:13]
	s_barrier
	ds_read_b128 v[166:169], v151 offset:49152
	ds_read_b128 v[170:173], v151 offset:50176
	ds_read_b128 v[174:177], v151 offset:51200
	ds_read_b128 v[178:181], v151 offset:52224
	ds_read_b128 v[186:189], v151 offset:53248
	ds_read_b128 v[190:193], v151 offset:54272
	ds_read_b128 v[194:197], v151 offset:55296
	ds_read_b128 v[198:201], v151 offset:56320
	global_load_lds_dwordx4 v[144:145], off
	v_lshl_add_u64 v[144:145], v[220:221], 0, s[12:13]
	s_mov_b32 m0, s50
	s_nop 0
	global_load_lds_dwordx4 v[144:145], off
	s_barrier
; __device__ __forceinline__ unsigned cvt_pk_bf16(float lo, float hi) { const f32v2_t v = {lo, hi}; const bf16v2_t r = __builtin_convertvector(v, bf16v2_t); return __builtin_bit_cast(unsigned, r); }
; __device__ __forceinline__ float bf2f(short b) { return __uint_as_float(((unsigned)(unsigned short)b) << 16); }
; #define PG8_STAGE(bufoff, gbase, voff) do { _Pragma("unroll") for (int _i = 0; _i < 2; ++_i) \
;         __builtin_amdgcn_global_load_lds((const unsigned*)((const char*)(gbase) + (voff)[_i]), (LAS unsigned*)(lds + (bufoff) + ldsw + _i * 8192), 16, 0, 0); } while (0)
; #define PG8_MMA(ai, bj, At, Bt) do { __builtin_amdgcn_s_setprio(1); _Pragma("unroll") for (int m = 0; m < 4; ++m) _Pragma("unroll") for (int n = 0; n < 2; ++n) _Pragma("unroll") for (int k = 0; k < 2; ++k) \
;         acc[ai][bj][m][n] = __builtin_amdgcn_mfma_f32_16x16x32_bf16(Bt[n][k], At[m][k], acc[ai][bj][m][n], 0, 0, 0); __builtin_amdgcn_s_setprio(0); } while (0)
; #define PG8_WAIT_V(n) asm volatile("s_waitcnt vmcnt(" #n ")" ::: "memory")
; template <class Epi>
; __device__ __forceinline__ void gemm_phase(LAS unsigned char* lds, const Gemm g, const StaticOrder& S, const Epi& E) {
;     ...
;             PG8_BAR; PG8_WAIT_L(0); PG8_MMA(1, 0, At, B0); PG8_BAR; PG8_SCHED;
;             PG8_STAGE(PG8_SB(1, 1), b3 + hstepB, voffB);
;             PG8_WAIT_V(6); PG8_BAR; PG8_MMA(1, 1, At, B1); PG8_BAR;
;         }
;         E(acc, cur, wr, wc, fr, fq);
;         if (!has_next) break;
;     __device__ __forceinline__ void operator()(const f32x4 (&acc)[2][2][4][2], const Unit& u, int wr, int wc, int fr, int fq) const {
;     ...
;                     for (int n = 0; n < 2; ++n) {
;                         if constexpr (NORM) {
;                             const f32x4 bv = *(const f32x4*)(bb + ro + bj * HALF + n * 16); const f32x4 v = acc[ai][bj][m][n] + bv;
;                             ss += (v[0] * v[0] + v[1] * v[1]) + (v[2] * v[2] + v[3] * v[3]);
;                             u32x2 w; w.x = cvt_pk_bf16(v[0], v[1]); w.y = cvt_pk_bf16(v[2], v[3]); *(u32x2*)(a3 + ro + bj * HALF + n * 16) = w;
;                         } else {
;                             const bf16x4 hb = *(const bf16x4*)(a3 + ro + bj * HALF + n * 16);
;                             *(f32x4*)(out + ro + bj * HALF + n * 16) = acc[ai][bj][m][n] + (f32x4){bf2f(hb[0]), bf2f(hb[1]), bf2f(hb[2]), bf2f(hb[3])}; } }
	s_waitcnt lgkmcnt(0)
	s_setprio 1
	s_waitcnt lgkmcnt(0)
	v_mfma_f32_16x16x32_bf16 v[60:63], v[140:143], v[166:169], v[60:63]
	v_mfma_f32_16x16x32_bf16 v[56:59], v[158:161], v[166:169], v[56:59]
	v_mfma_f32_16x16x32_bf16 v[48:51], v[140:143], v[174:177], v[48:51]
	v_mfma_f32_16x16x32_bf16 v[40:43], v[158:161], v[174:177], v[40:43]
	v_mfma_f32_16x16x32_bf16 v[32:35], v[140:143], v[186:189], v[32:35]
	v_mfma_f32_16x16x32_bf16 v[24:27], v[158:161], v[186:189], v[24:27]
	v_mfma_f32_16x16x32_bf16 v[16:19], v[140:143], v[194:197], v[16:19]
	v_mfma_f32_16x16x32_bf16 v[8:11], v[158:161], v[194:197], v[8:11]
	v_mfma_f32_16x16x32_bf16 v[60:63], v[154:157], v[170:173], v[60:63]
	v_mfma_f32_16x16x32_bf16 v[56:59], v[162:165], v[170:173], v[56:59]
	v_mfma_f32_16x16x32_bf16 v[48:51], v[154:157], v[178:181], v[48:51]
	v_mfma_f32_16x16x32_bf16 v[40:43], v[162:165], v[178:181], v[40:43]
	v_mfma_f32_16x16x32_bf16 v[32:35], v[154:157], v[190:193], v[32:35]
	v_mfma_f32_16x16x32_bf16 v[24:27], v[162:165], v[190:193], v[24:27]
	v_mfma_f32_16x16x32_bf16 v[16:19], v[154:157], v[198:201], v[16:19]
	v_mfma_f32_16x16x32_bf16 v[8:11], v[162:165], v[198:201], v[8:11]
	s_setprio 0
	s_barrier
	s_add_u32 s38, s38, 0x40080
	s_addc_u32 s39, s39, 0
	s_add_i32 s40, s40, s42
	v_lshl_add_u64 v[140:141], s[38:39], 0, v[128:129]
	s_mov_b32 m0, s40
	s_nop 0
	global_load_lds_dwordx4 v[140:141], off
	v_lshl_add_u64 v[140:141], s[38:39], 0, v[130:131]
	s_add_i32 m0, s40, 0x2000
	s_nop 0
	global_load_lds_dwordx4 v[140:141], off
	s_waitcnt vmcnt(6)
	s_barrier
	s_setprio 1
	v_mfma_f32_16x16x32_bf16 v[52:55], v[202:205], v[166:169], v[52:55]
	v_mfma_f32_16x16x32_bf16 v[44:47], v[210:213], v[166:169], v[44:47]
	v_mfma_f32_16x16x32_bf16 v[36:39], v[202:205], v[174:177], v[36:39]
	v_mfma_f32_16x16x32_bf16 v[28:31], v[210:213], v[174:177], v[28:31]
	v_mfma_f32_16x16x32_bf16 v[20:23], v[202:205], v[186:189], v[20:23]
	v_mfma_f32_16x16x32_bf16 v[12:15], v[210:213], v[186:189], v[12:15]
	v_mfma_f32_16x16x32_bf16 v[4:7], v[202:205], v[194:197], v[4:7]
	v_mfma_f32_16x16x32_bf16 v[0:3], v[210:213], v[194:197], v[0:3]
	v_mfma_f32_16x16x32_bf16 v[52:55], v[206:209], v[170:173], v[52:55]
	v_mfma_f32_16x16x32_bf16 v[44:47], v[214:217], v[170:173], v[44:47]
	v_mfma_f32_16x16x32_bf16 v[36:39], v[206:209], v[178:181], v[36:39]
	v_mfma_f32_16x16x32_bf16 v[28:31], v[214:217], v[178:181], v[28:31]
	v_mfma_f32_16x16x32_bf16 v[20:23], v[206:209], v[190:193], v[20:23]
	v_mfma_f32_16x16x32_bf16 v[12:15], v[214:217], v[190:193], v[12:15]
	v_mfma_f32_16x16x32_bf16 v[4:7], v[206:209], v[198:201], v[4:7]
	v_mfma_f32_16x16x32_bf16 v[0:3], v[214:217], v[198:201], v[0:3]
	s_setprio 0
	s_add_i32 s59, s59, 2
	s_add_u32 s36, s36, 0x100
	s_addc_u32 s37, s37, 0
	s_add_u32 s57, s57, 0x100
	s_addc_u32 s58, s58, 0
	s_cmp_gt_u32 s59, 13
	s_barrier
	s_cbranch_scc0 .LBB0_1478
	v_lshl_add_u32 v144, s34, 8, v147
	v_lshl_or_b32 v142, s54, 8, v149
	v_ashrrev_i32_e32 v145, 31, v144
	v_ashrrev_i32_e32 v143, 31, v142
	v_lshlrev_b64 v[140:141], 10, v[144:145]
	v_lshl_add_u64 v[140:141], v[140:141], 0, v[142:143]
	s_and_b64 vcc, exec, s[0:1]
	s_mov_b32 s54, s22
	s_mov_b32 s34, s24
	s_mov_b64 s[38:39], s[28:29]
	s_mov_b64 s[36:37], s[26:27]
	s_mov_b64 s[60:61], 0x8000
	s_mov_b64 s[62:63], 0x28000
	s_mov_b64 s[64:65], 0x10000
	s_mov_b64 s[66:67], 0x50000
	v_lshl_add_u64 v[142:143], v[140:141], 1, s[4:5]
	v_lshl_add_u64 v[144:145], v[140:141], 2, s[48:49]
	global_load_dwordx2 v[154:155], v[142:143], off
	global_load_dwordx2 v[156:157], v[142:143], off offset:32
	global_load_dwordx2 v[158:159], v[142:143], off offset:256
	global_load_dwordx2 v[160:161], v[142:143], off offset:288
	v_lshl_add_u64 v[142:143], v[142:143], 0, s[60:61]
	global_load_dwordx2 v[162:163], v[142:143], off
	global_load_dwordx2 v[164:165], v[142:143], off offset:32
	global_load_dwordx2 v[166:167], v[142:143], off offset:256
	global_load_dwordx2 v[168:169], v[142:143], off offset:288
	v_lshl_add_u64 v[142:143], v[142:143], 0, s[60:61]
	global_load_dwordx2 v[170:171], v[142:143], off
	global_load_dwordx2 v[172:173], v[142:143], off offset:32
	global_load_dwordx2 v[174:175], v[142:143], off offset:256
	global_load_dwordx2 v[176:177], v[142:143], off offset:288
	v_lshl_add_u64 v[142:143], v[142:143], 0, s[60:61]
	global_load_dwordx2 v[178:179], v[142:143], off
	global_load_dwordx2 v[180:181], v[142:143], off offset:32
	global_load_dwordx2 v[182:183], v[142:143], off offset:256
	global_load_dwordx2 v[186:187], v[142:143], off offset:288
	v_lshl_add_u64 v[142:143], v[142:143], 0, s[62:63]
	global_load_dwordx2 v[188:189], v[142:143], off
	global_load_dwordx2 v[190:191], v[142:143], off offset:32
	global_load_dwordx2 v[192:193], v[142:143], off offset:256
	global_load_dwordx2 v[194:195], v[142:143], off offset:288
	v_lshl_add_u64 v[142:143], v[142:143], 0, s[60:61]
	global_load_dwordx2 v[196:197], v[142:143], off
	global_load_dwordx2 v[198:199], v[142:143], off offset:32
	global_load_dwordx2 v[200:201], v[142:143], off offset:256
	global_load_dwordx2 v[202:203], v[142:143], off offset:288
	v_lshl_add_u64 v[142:143], v[142:143], 0, s[60:61]
	global_load_dwordx2 v[204:205], v[142:143], off
	global_load_dwordx2 v[206:207], v[142:143], off offset:32
	global_load_dwordx2 v[208:209], v[142:143], off offset:256
	global_load_dwordx2 v[210:211], v[142:143], off offset:288
	v_lshl_add_u64 v[142:143], v[142:143], 0, s[60:61]
	global_load_dwordx2 v[212:213], v[142:143], off
	global_load_dwordx2 v[214:215], v[142:143], off offset:32
	global_load_dwordx2 v[216:217], v[142:143], off offset:256
	global_load_dwordx2 v[218:219], v[142:143], off offset:288
	s_waitcnt vmcnt(31)
; __device__ __forceinline__ unsigned cvt_pk_bf16(float lo, float hi) { const f32v2_t v = {lo, hi}; const bf16v2_t r = __builtin_convertvector(v, bf16v2_t); return __builtin_bit_cast(unsigned, r); }
; __device__ __forceinline__ float bf2f(short b) { return __uint_as_float(((unsigned)(unsigned short)b) << 16); }
;     __device__ __forceinline__ void operator()(const f32x4 (&acc)[2][2][4][2], const Unit& u, int wr, int wc, int fr, int fq) const {
;     ...
;                     for (int n = 0; n < 2; ++n) {
;                         if constexpr (NORM) {
;                             const f32x4 bv = *(const f32x4*)(bb + ro + bj * HALF + n * 16); const f32x4 v = acc[ai][bj][m][n] + bv;
;                             ss += (v[0] * v[0] + v[1] * v[1]) + (v[2] * v[2] + v[3] * v[3]);
;                             u32x2 w; w.x = cvt_pk_bf16(v[0], v[1]); w.y = cvt_pk_bf16(v[2], v[3]); *(u32x2*)(a3 + ro + bj * HALF + n * 16) = w;
;                         } else {
;                             const bf16x4 hb = *(const bf16x4*)(a3 + ro + bj * HALF + n * 16);
;                             *(f32x4*)(out + ro + bj * HALF + n * 16) = acc[ai][bj][m][n] + (f32x4){bf2f(hb[0]), bf2f(hb[1]), bf2f(hb[2]), bf2f(hb[3])}; } }
	v_and_b32_e32 v141, 0xffff0000, v155
	v_lshlrev_b32_e32 v140, 16, v155
	v_and_b32_e32 v155, 0xffff0000, v154
	v_lshlrev_b32_e32 v154, 16, v154
	v_pk_add_f32 v[124:125], v[124:125], v[154:155]
	v_pk_add_f32 v[126:127], v[126:127], v[140:141]
	global_store_dwordx4 v[144:145], v[124:127], off nt
	s_waitcnt vmcnt(31)
	v_and_b32_e32 v141, 0xffff0000, v157
	v_lshlrev_b32_e32 v140, 16, v157
	v_and_b32_e32 v157, 0xffff0000, v156
	v_lshlrev_b32_e32 v156, 16, v156
	v_pk_add_f32 v[120:121], v[120:121], v[156:157]
	v_pk_add_f32 v[122:123], v[122:123], v[140:141]
	global_store_dwordx4 v[144:145], v[120:123], off offset:64 nt
	s_waitcnt vmcnt(31)
	v_and_b32_e32 v141, 0xffff0000, v159
	v_lshlrev_b32_e32 v140, 16, v159
	v_and_b32_e32 v159, 0xffff0000, v158
	v_lshlrev_b32_e32 v158, 16, v158
	v_pk_add_f32 v[116:117], v[116:117], v[158:159]
	v_pk_add_f32 v[118:119], v[118:119], v[140:141]
	global_store_dwordx4 v[144:145], v[116:119], off offset:512 nt
	s_waitcnt vmcnt(31)
	v_and_b32_e32 v141, 0xffff0000, v161
	v_lshlrev_b32_e32 v140, 16, v161
	v_and_b32_e32 v161, 0xffff0000, v160
	v_lshlrev_b32_e32 v160, 16, v160
	v_pk_add_f32 v[108:109], v[108:109], v[160:161]
	v_pk_add_f32 v[110:111], v[110:111], v[140:141]
	global_store_dwordx4 v[144:145], v[108:111], off offset:576 nt
	v_lshl_add_u64 v[144:145], v[144:145], 0, s[64:65]
	s_waitcnt vmcnt(31)
	v_and_b32_e32 v141, 0xffff0000, v163
	v_lshlrev_b32_e32 v140, 16, v163
	v_and_b32_e32 v163, 0xffff0000, v162
	v_lshlrev_b32_e32 v162, 16, v162
	v_pk_add_f32 v[112:113], v[112:113], v[162:163]
	v_pk_add_f32 v[114:115], v[114:115], v[140:141]
	global_store_dwordx4 v[144:145], v[112:115], off nt
	s_waitcnt vmcnt(31)
	v_and_b32_e32 v141, 0xffff0000, v165
	v_lshlrev_b32_e32 v140, 16, v165
	v_and_b32_e32 v165, 0xffff0000, v164
	v_lshlrev_b32_e32 v164, 16, v164
	v_pk_add_f32 v[104:105], v[104:105], v[164:165]
	v_pk_add_f32 v[106:107], v[106:107], v[140:141]
	global_store_dwordx4 v[144:145], v[104:107], off offset:64 nt
	s_waitcnt vmcnt(31)
	v_and_b32_e32 v141, 0xffff0000, v167
	v_lshlrev_b32_e32 v140, 16, v167
	v_and_b32_e32 v167, 0xffff0000, v166
	v_lshlrev_b32_e32 v166, 16, v166
	v_pk_add_f32 v[100:101], v[100:101], v[166:167]
	v_pk_add_f32 v[102:103], v[102:103], v[140:141]
	global_store_dwordx4 v[144:145], v[100:103], off offset:512 nt
	s_waitcnt vmcnt(31)
	v_and_b32_e32 v141, 0xffff0000, v169
	v_lshlrev_b32_e32 v140, 16, v169
	v_and_b32_e32 v169, 0xffff0000, v168
	v_lshlrev_b32_e32 v168, 16, v168
	v_pk_add_f32 v[92:93], v[92:93], v[168:169]
	v_pk_add_f32 v[94:95], v[94:95], v[140:141]
	global_store_dwordx4 v[144:145], v[92:95], off offset:576 nt
	v_lshl_add_u64 v[144:145], v[144:145], 0, s[64:65]
	s_waitcnt vmcnt(31)
	v_and_b32_e32 v141, 0xffff0000, v171
	v_lshlrev_b32_e32 v140, 16, v171
	v_and_b32_e32 v171, 0xffff0000, v170
	v_lshlrev_b32_e32 v170, 16, v170
	v_pk_add_f32 v[96:97], v[96:97], v[170:171]
	v_pk_add_f32 v[98:99], v[98:99], v[140:141]
	global_store_dwordx4 v[144:145], v[96:99], off nt
	s_waitcnt vmcnt(31)
	v_and_b32_e32 v141, 0xffff0000, v173
	v_lshlrev_b32_e32 v140, 16, v173
	v_and_b32_e32 v173, 0xffff0000, v172
	v_lshlrev_b32_e32 v172, 16, v172
	v_pk_add_f32 v[88:89], v[88:89], v[172:173]
	v_pk_add_f32 v[90:91], v[90:91], v[140:141]
	global_store_dwordx4 v[144:145], v[88:91], off offset:64 nt
	s_waitcnt vmcnt(31)
	v_and_b32_e32 v141, 0xffff0000, v175
	v_lshlrev_b32_e32 v140, 16, v175
	v_and_b32_e32 v175, 0xffff0000, v174
	v_lshlrev_b32_e32 v174, 16, v174
	v_pk_add_f32 v[84:85], v[84:85], v[174:175]
	v_pk_add_f32 v[86:87], v[86:87], v[140:141]
	global_store_dwordx4 v[144:145], v[84:87], off offset:512 nt
	s_waitcnt vmcnt(31)
	v_and_b32_e32 v141, 0xffff0000, v177
	v_lshlrev_b32_e32 v140, 16, v177
	v_and_b32_e32 v177, 0xffff0000, v176
	v_lshlrev_b32_e32 v176, 16, v176
	v_pk_add_f32 v[76:77], v[76:77], v[176:177]
	v_pk_add_f32 v[78:79], v[78:79], v[140:141]
	global_store_dwordx4 v[144:145], v[76:79], off offset:576 nt
	v_lshl_add_u64 v[144:145], v[144:145], 0, s[64:65]
	s_waitcnt vmcnt(31)
	v_and_b32_e32 v141, 0xffff0000, v179
	v_lshlrev_b32_e32 v140, 16, v179
	v_and_b32_e32 v179, 0xffff0000, v178
	v_lshlrev_b32_e32 v178, 16, v178
	v_pk_add_f32 v[80:81], v[80:81], v[178:179]
	v_pk_add_f32 v[82:83], v[82:83], v[140:141]
	global_store_dwordx4 v[144:145], v[80:83], off nt
	s_waitcnt vmcnt(31)
	v_and_b32_e32 v141, 0xffff0000, v181
	v_lshlrev_b32_e32 v140, 16, v181
	v_and_b32_e32 v181, 0xffff0000, v180
	v_lshlrev_b32_e32 v180, 16, v180
	v_pk_add_f32 v[72:73], v[72:73], v[180:181]
	v_pk_add_f32 v[74:75], v[74:75], v[140:141]
	global_store_dwordx4 v[144:145], v[72:75], off offset:64 nt
	s_waitcnt vmcnt(31)
	v_and_b32_e32 v141, 0xffff0000, v183
	v_lshlrev_b32_e32 v140, 16, v183
	v_and_b32_e32 v183, 0xffff0000, v182
	v_lshlrev_b32_e32 v182, 16, v182
	v_pk_add_f32 v[68:69], v[68:69], v[182:183]
	v_pk_add_f32 v[70:71], v[70:71], v[140:141]
	global_store_dwordx4 v[144:145], v[68:71], off offset:512 nt
	s_waitcnt vmcnt(31)
	v_and_b32_e32 v141, 0xffff0000, v187
	v_lshlrev_b32_e32 v140, 16, v187
	v_and_b32_e32 v187, 0xffff0000, v186
	v_lshlrev_b32_e32 v186, 16, v186
	v_pk_add_f32 v[64:65], v[64:65], v[186:187]
	v_pk_add_f32 v[66:67], v[66:67], v[140:141]
	global_store_dwordx4 v[144:145], v[64:67], off offset:576 nt
	v_lshl_add_u64 v[144:145], v[144:145], 0, s[66:67]
	s_waitcnt vmcnt(31)
; __device__ __forceinline__ unsigned cvt_pk_bf16(float lo, float hi) { const f32v2_t v = {lo, hi}; const bf16v2_t r = __builtin_convertvector(v, bf16v2_t); return __builtin_bit_cast(unsigned, r); }
; __device__ __forceinline__ float bf2f(short b) { return __uint_as_float(((unsigned)(unsigned short)b) << 16); }
; #define PG8_WAIT_V(n) asm volatile("s_waitcnt vmcnt(" #n ")" ::: "memory")
; #define PG8_BAR __builtin_amdgcn_s_barrier()
; template <class Epi>
; __device__ __forceinline__ void gemm_phase(LAS unsigned char* lds, const Gemm g, const StaticOrder& S, const Epi& E) {
;     ...
;         if (!has_next) break;
; #pragma unroll
;         for (int a = 0; a < 2; ++a)
; #pragma unroll
;             for (int b = 0; b < 2; ++b)
; #pragma unroll
;                 for (int m = 0; m < 4; ++m)
; #pragma unroll
;                     for (int n = 0; n < 2; ++n) acc[a][b][m][n] = (f32x4){0.f, 0.f, 0.f, 0.f};
;         cur = nxt; cA = nA; cB = nB; ++ui;
;     }
;     PG8_WAIT_V(0);
;     if (wr == 0) PG8_BAR;
;     PG8_BAR;
;     __device__ __forceinline__ void operator()(const f32x4 (&acc)[2][2][4][2], const Unit& u, int wr, int wc, int fr, int fq) const {
;     ...
;                     for (int n = 0; n < 2; ++n) {
;                         if constexpr (NORM) {
;                             const f32x4 bv = *(const f32x4*)(bb + ro + bj * HALF + n * 16); const f32x4 v = acc[ai][bj][m][n] + bv;
;                             ss += (v[0] * v[0] + v[1] * v[1]) + (v[2] * v[2] + v[3] * v[3]);
;                             u32x2 w; w.x = cvt_pk_bf16(v[0], v[1]); w.y = cvt_pk_bf16(v[2], v[3]); *(u32x2*)(a3 + ro + bj * HALF + n * 16) = w;
;                         } else {
;                             const bf16x4 hb = *(const bf16x4*)(a3 + ro + bj * HALF + n * 16);
;                             *(f32x4*)(out + ro + bj * HALF + n * 16) = acc[ai][bj][m][n] + (f32x4){bf2f(hb[0]), bf2f(hb[1]), bf2f(hb[2]), bf2f(hb[3])}; } }
	v_and_b32_e32 v141, 0xffff0000, v189
	v_lshlrev_b32_e32 v140, 16, v189
	v_and_b32_e32 v189, 0xffff0000, v188
	v_lshlrev_b32_e32 v188, 16, v188
	v_pk_add_f32 v[60:61], v[60:61], v[188:189]
	v_pk_add_f32 v[62:63], v[62:63], v[140:141]
	global_store_dwordx4 v[144:145], v[60:63], off nt
	s_waitcnt vmcnt(31)
	v_and_b32_e32 v141, 0xffff0000, v191
	v_lshlrev_b32_e32 v140, 16, v191
	v_and_b32_e32 v191, 0xffff0000, v190
	v_lshlrev_b32_e32 v190, 16, v190
	v_pk_add_f32 v[56:57], v[56:57], v[190:191]
	v_pk_add_f32 v[58:59], v[58:59], v[140:141]
	global_store_dwordx4 v[144:145], v[56:59], off offset:64 nt
	s_waitcnt vmcnt(31)
	v_and_b32_e32 v141, 0xffff0000, v193
	v_lshlrev_b32_e32 v140, 16, v193
	v_and_b32_e32 v193, 0xffff0000, v192
	v_lshlrev_b32_e32 v192, 16, v192
	v_pk_add_f32 v[52:53], v[52:53], v[192:193]
	v_pk_add_f32 v[54:55], v[54:55], v[140:141]
	global_store_dwordx4 v[144:145], v[52:55], off offset:512 nt
	s_waitcnt vmcnt(31)
	v_and_b32_e32 v141, 0xffff0000, v195
	v_lshlrev_b32_e32 v140, 16, v195
	v_and_b32_e32 v195, 0xffff0000, v194
	v_lshlrev_b32_e32 v194, 16, v194
	v_pk_add_f32 v[44:45], v[44:45], v[194:195]
	v_pk_add_f32 v[46:47], v[46:47], v[140:141]
	global_store_dwordx4 v[144:145], v[44:47], off offset:576 nt
	v_lshl_add_u64 v[144:145], v[144:145], 0, s[64:65]
	s_waitcnt vmcnt(31)
	v_and_b32_e32 v141, 0xffff0000, v197
	v_lshlrev_b32_e32 v140, 16, v197
	v_and_b32_e32 v197, 0xffff0000, v196
	v_lshlrev_b32_e32 v196, 16, v196
	v_pk_add_f32 v[48:49], v[48:49], v[196:197]
	v_pk_add_f32 v[50:51], v[50:51], v[140:141]
	global_store_dwordx4 v[144:145], v[48:51], off nt
	s_waitcnt vmcnt(31)
	v_and_b32_e32 v141, 0xffff0000, v199
	v_lshlrev_b32_e32 v140, 16, v199
	v_and_b32_e32 v199, 0xffff0000, v198
	v_lshlrev_b32_e32 v198, 16, v198
	v_pk_add_f32 v[40:41], v[40:41], v[198:199]
	v_pk_add_f32 v[42:43], v[42:43], v[140:141]
	global_store_dwordx4 v[144:145], v[40:43], off offset:64 nt
	s_waitcnt vmcnt(31)
	v_and_b32_e32 v141, 0xffff0000, v201
	v_lshlrev_b32_e32 v140, 16, v201
	v_and_b32_e32 v201, 0xffff0000, v200
	v_lshlrev_b32_e32 v200, 16, v200
	v_pk_add_f32 v[36:37], v[36:37], v[200:201]
	v_pk_add_f32 v[38:39], v[38:39], v[140:141]
	global_store_dwordx4 v[144:145], v[36:39], off offset:512 nt
	s_waitcnt vmcnt(31)
	v_and_b32_e32 v141, 0xffff0000, v203
	v_lshlrev_b32_e32 v140, 16, v203
	v_and_b32_e32 v203, 0xffff0000, v202
	v_lshlrev_b32_e32 v202, 16, v202
	v_pk_add_f32 v[28:29], v[28:29], v[202:203]
	v_pk_add_f32 v[30:31], v[30:31], v[140:141]
	global_store_dwordx4 v[144:145], v[28:31], off offset:576 nt
	v_lshl_add_u64 v[144:145], v[144:145], 0, s[64:65]
	s_waitcnt vmcnt(31)
	v_and_b32_e32 v141, 0xffff0000, v205
	v_lshlrev_b32_e32 v140, 16, v205
	v_and_b32_e32 v205, 0xffff0000, v204
	v_lshlrev_b32_e32 v204, 16, v204
	v_pk_add_f32 v[32:33], v[32:33], v[204:205]
	v_pk_add_f32 v[34:35], v[34:35], v[140:141]
	global_store_dwordx4 v[144:145], v[32:35], off nt
	s_waitcnt vmcnt(31)
	v_and_b32_e32 v141, 0xffff0000, v207
	v_lshlrev_b32_e32 v140, 16, v207
	v_and_b32_e32 v207, 0xffff0000, v206
	v_lshlrev_b32_e32 v206, 16, v206
	v_pk_add_f32 v[24:25], v[24:25], v[206:207]
	v_pk_add_f32 v[26:27], v[26:27], v[140:141]
	global_store_dwordx4 v[144:145], v[24:27], off offset:64 nt
	s_waitcnt vmcnt(31)
	v_and_b32_e32 v141, 0xffff0000, v209
	v_lshlrev_b32_e32 v140, 16, v209
	v_and_b32_e32 v209, 0xffff0000, v208
	v_lshlrev_b32_e32 v208, 16, v208
	v_pk_add_f32 v[20:21], v[20:21], v[208:209]
	v_pk_add_f32 v[22:23], v[22:23], v[140:141]
	global_store_dwordx4 v[144:145], v[20:23], off offset:512 nt
	s_waitcnt vmcnt(31)
	v_and_b32_e32 v141, 0xffff0000, v211
	v_lshlrev_b32_e32 v140, 16, v211
	v_and_b32_e32 v211, 0xffff0000, v210
	v_lshlrev_b32_e32 v210, 16, v210
	v_pk_add_f32 v[12:13], v[12:13], v[210:211]
	v_pk_add_f32 v[14:15], v[14:15], v[140:141]
	global_store_dwordx4 v[144:145], v[12:15], off offset:576 nt
	v_lshl_add_u64 v[144:145], v[144:145], 0, s[64:65]
	s_waitcnt vmcnt(31)
	v_and_b32_e32 v141, 0xffff0000, v213
	v_lshlrev_b32_e32 v140, 16, v213
	v_and_b32_e32 v213, 0xffff0000, v212
	v_lshlrev_b32_e32 v212, 16, v212
	v_pk_add_f32 v[16:17], v[16:17], v[212:213]
	v_pk_add_f32 v[18:19], v[18:19], v[140:141]
	global_store_dwordx4 v[144:145], v[16:19], off nt
	s_waitcnt vmcnt(31)
	v_and_b32_e32 v141, 0xffff0000, v215
	v_lshlrev_b32_e32 v140, 16, v215
	v_and_b32_e32 v215, 0xffff0000, v214
	v_lshlrev_b32_e32 v214, 16, v214
	v_pk_add_f32 v[8:9], v[8:9], v[214:215]
	v_pk_add_f32 v[10:11], v[10:11], v[140:141]
	global_store_dwordx4 v[144:145], v[8:11], off offset:64 nt
	s_waitcnt vmcnt(31)
	v_and_b32_e32 v141, 0xffff0000, v217
	v_lshlrev_b32_e32 v140, 16, v217
	v_and_b32_e32 v217, 0xffff0000, v216
	v_lshlrev_b32_e32 v216, 16, v216
	v_pk_add_f32 v[4:5], v[4:5], v[216:217]
	v_pk_add_f32 v[6:7], v[6:7], v[140:141]
	global_store_dwordx4 v[144:145], v[4:7], off offset:512 nt
	s_waitcnt vmcnt(31)
	v_and_b32_e32 v141, 0xffff0000, v219
	v_lshlrev_b32_e32 v140, 16, v219
	v_and_b32_e32 v219, 0xffff0000, v218
	v_lshlrev_b32_e32 v218, 16, v218
	v_pk_add_f32 v[0:1], v[0:1], v[218:219]
	v_pk_add_f32 v[2:3], v[2:3], v[140:141]
	global_store_dwordx4 v[144:145], v[0:3], off offset:576 nt
	s_cbranch_vccz .LBB0_1471
	s_waitcnt vmcnt(0)
	s_cmpk_gt_u32 s30, 0xff
	s_cbranch_scc1 .LBB0_1482
	s_barrier
